# v132 + differential-attention key loop unrolled by two with the two packed-P register sets exchanged in the second copy: no per-iteration 16-register P copy in the steady state
# speedup vs baseline: 1.0058x; 1.0058x over previous
.LBB0_567:
	s_waitcnt lgkmcnt(3)
	v_mfma_f32_32x32x16_bf16 v[32:47], v[124:127], v[172:175], v[32:47]
	ds_read_b128 v[188:191], v247 offset:9216
	ds_read_b128 v[184:187], v247 offset:9248
	ds_read_b128 v[180:183], v247 offset:9280
	ds_read_b128 v[176:179], v247 offset:9312
	v_exp_f32_e32 v200, v96
	v_exp_f32_e32 v201, v97
	v_exp_f32_e32 v202, v98
	v_exp_f32_e32 v203, v99
	v_cvt_pk_bf16_f32 v192, v200, v201
	v_cvt_pk_bf16_f32 v193, v202, v203
	s_waitcnt lgkmcnt(6)
	v_mfma_f32_32x32x16_bf16 v[32:47], v[120:123], v[168:171], v[32:47]
	v_exp_f32_e32 v124, v100
	v_exp_f32_e32 v125, v101
	v_exp_f32_e32 v126, v102
	v_exp_f32_e32 v127, v103
	v_cvt_pk_bf16_f32 v194, v124, v125
	v_cvt_pk_bf16_f32 v195, v126, v127
	s_waitcnt lgkmcnt(5)
	v_mfma_f32_32x32x16_bf16 v[32:47], v[116:119], v[164:167], v[32:47]
	v_exp_f32_e32 v120, v104
	v_exp_f32_e32 v121, v105
	v_exp_f32_e32 v122, v106
	v_exp_f32_e32 v123, v107
	v_cvt_pk_bf16_f32 v196, v120, v121
	v_cvt_pk_bf16_f32 v197, v122, v123
	s_waitcnt lgkmcnt(4)
	v_mfma_f32_32x32x16_bf16 v[32:47], v[112:115], v[160:163], v[32:47]
	v_exp_f32_e32 v116, v108
	v_exp_f32_e32 v117, v109
	v_exp_f32_e32 v118, v110
	v_exp_f32_e32 v119, v111
	v_cvt_pk_bf16_f32 v198, v116, v117
	v_cvt_pk_bf16_f32 v199, v118, v119
	v_add_f32_e32 v112, v202, v200
	v_add_f32_e32 v113, v203, v201
	s_waitcnt lgkmcnt(3)
	v_mfma_f32_32x32x16_bf16 v[16:31], v[188:191], v[172:175], v[16:31]
	v_add_f32_e32 v112, v124, v112
	v_add_f32_e32 v113, v125, v113
	ds_read_b128 v[96:99], v247 offset:13824
	ds_read_b128 v[100:103], v247 offset:13856
	ds_read_b128 v[104:107], v247 offset:13888
	ds_read_b128 v[108:111], v247 offset:13920
	v_add_f32_e32 v112, v126, v112
	v_add_f32_e32 v113, v127, v113
	v_exp_f32_e32 v80, v80
	v_exp_f32_e32 v81, v81
	v_add_f32_e32 v112, v120, v112
	v_add_f32_e32 v113, v121, v113
	v_cvt_pk_bf16_f32 v200, v80, v81
	v_add_f32_e32 v112, v122, v112
	v_add_f32_e32 v113, v123, v113
	v_add_f32_e32 v112, v116, v112
	v_add_f32_e32 v113, v117, v113
	v_add_f32_e32 v112, v118, v112
	v_add_f32_e32 v113, v119, v113
	v_add_f32_e32 v112, v80, v112
	v_add_f32_e32 v113, v81, v113
	s_waitcnt lgkmcnt(6)
	v_mfma_f32_32x32x16_bf16 v[16:31], v[184:187], v[168:171], v[16:31]
	v_exp_f32_e32 v80, v82
	v_exp_f32_e32 v81, v83
	v_add_f32_e32 v82, v80, v112
	v_cvt_pk_bf16_f32 v201, v80, v81
	v_add_f32_e32 v83, v81, v113
	s_waitcnt lgkmcnt(5)
	v_mfma_f32_32x32x16_bf16 v[16:31], v[180:183], v[164:167], v[16:31]
	v_exp_f32_e32 v80, v84
	v_exp_f32_e32 v81, v85
	v_add_f32_e32 v82, v80, v82
	v_cvt_pk_bf16_f32 v202, v80, v81
	v_add_f32_e32 v83, v81, v83
	s_waitcnt lgkmcnt(4)
	v_mfma_f32_32x32x16_bf16 v[16:31], v[176:179], v[160:163], v[16:31]
	v_exp_f32_e32 v80, v86
	v_exp_f32_e32 v81, v87
	v_add_f32_e32 v82, v80, v82
	v_cvt_pk_bf16_f32 v203, v80, v81
	v_add_f32_e32 v83, v81, v83
	s_waitcnt lgkmcnt(3)
	v_mfma_f32_32x32x16_bf16 v[0:15], v[96:99], v[172:175], v[0:15]
	v_exp_f32_e32 v80, v88
	v_exp_f32_e32 v81, v89
	v_add_f32_e32 v82, v80, v82
	v_cvt_pk_bf16_f32 v204, v80, v81
	v_add_f32_e32 v83, v81, v83
	s_waitcnt lgkmcnt(2)
	v_mfma_f32_32x32x16_bf16 v[0:15], v[100:103], v[168:171], v[0:15]
	v_exp_f32_e32 v80, v90
	v_exp_f32_e32 v81, v91
	v_add_f32_e32 v82, v80, v82
	v_cvt_pk_bf16_f32 v205, v80, v81
	v_add_f32_e32 v83, v81, v83
	s_waitcnt lgkmcnt(1)
	v_mfma_f32_32x32x16_bf16 v[0:15], v[104:107], v[164:167], v[0:15]
	v_exp_f32_e32 v80, v92
	v_exp_f32_e32 v81, v93
	v_add_f32_e32 v82, v80, v82
	v_cvt_pk_bf16_f32 v206, v80, v81
	v_add_f32_e32 v83, v81, v83
	s_waitcnt lgkmcnt(0)
	v_mfma_f32_32x32x16_bf16 v[0:15], v[108:111], v[160:163], v[0:15]
	v_exp_f32_e32 v80, v94
	v_exp_f32_e32 v81, v95
	v_add_f32_e32 v82, v80, v82
	v_cvt_pk_bf16_f32 v207, v80, v81
	v_add_f32_e32 v83, v81, v83
	v_add_f32_e32 v252, v82, v83
	v_fmac_f32_e32 v252, v223, v224
	s_branch .LBB0_570

.LBB0_571:
	s_mul_hi_u32 s40, s72, 0xaaaaaaab
	s_lshr_b32 s40, s40, 1
	s_mul_i32 s40, s40, 0xd800
	s_bitcmp1_b32 s72, 0
	v_subrev_u32_e32 v80, s40, v222
	s_cselect_b32 s40, 0x4400, 0
	v_add_u32_e32 v81, s40, v234
	s_add_i32 s40, s73, 0
	v_add_u32_e32 v80, s40, v80
	s_waitcnt vmcnt(3)
	ds_write_b128 v81, v[144:147]
	s_waitcnt vmcnt(2)
	ds_write_b128 v80, v[148:151] offset:53248
	s_waitcnt vmcnt(1)
	ds_write_b128 v81, v[152:155] offset:8704
	s_waitcnt vmcnt(0)
	ds_write_b128 v80, v[156:159] offset:62464
	s_branch .Ldfu_554
.Ldfu_554:
	s_sub_i32 s71, s71, 64
	s_addk_i32 s73, 0x4800
	s_add_i32 s72, s72, 1
	s_add_i32 s74, s74, 1
	s_add_i32 s4, s4, -1
	s_cmpk_eq_i32 s71, 0xff80
	s_waitcnt lgkmcnt(0)
	s_barrier
	s_cbranch_scc1 .LBB0_572

.Ldfu_560:
	s_xor_b64 s[84:85], s[42:43], -1
	s_waitcnt lgkmcnt(7)
	v_mfma_f32_32x32x16_bf16 v[96:111], v[92:95], v[136:139], v[64:79]
	s_mov_b64 s[42:43], -1
	s_andn2_b64 vcc, exec, s[84:85]
	s_waitcnt lgkmcnt(6)
	v_mfma_f32_32x32x16_bf16 v[96:111], v[88:91], v[128:131], v[96:111]
	s_waitcnt lgkmcnt(5)
	v_mfma_f32_32x32x16_bf16 v[96:111], v[84:87], v[132:135], v[96:111]
	s_waitcnt lgkmcnt(4)
	v_mfma_f32_32x32x16_bf16 v[96:111], v[80:83], v[140:143], v[96:111]
	s_waitcnt lgkmcnt(3)
	v_mfma_f32_32x32x16_bf16 v[80:95], v[120:123], v[136:139], v[64:79]
	s_waitcnt lgkmcnt(2)
	v_mfma_f32_32x32x16_bf16 v[80:95], v[116:119], v[128:131], v[80:95]
	s_waitcnt lgkmcnt(1)
	v_mfma_f32_32x32x16_bf16 v[80:95], v[112:115], v[132:135], v[80:95]
	s_waitcnt lgkmcnt(0)
	v_mfma_f32_32x32x16_bf16 v[80:95], v[208:211], v[140:143], v[80:95]
	s_cbranch_vccnz .Ldfu_562
	v_add_u32_e32 v112, s71, v232
	v_add_u32_e32 v113, 64, v112
	v_cmp_le_i32_e32 vcc, v113, v212
	v_add_u32_e32 v116, 0x42, v112
	v_add_u32_e32 v117, 0x43, v112
	v_cndmask_b32_e32 v114, v229, v96, vcc
	v_cmp_lt_i32_e32 vcc, v113, v212
	v_add_u32_e32 v118, 0x48, v112
	v_add_u32_e32 v119, 0x49, v112
	v_cndmask_b32_e32 v113, v229, v97, vcc
	v_cmp_le_i32_e32 vcc, v116, v212
	v_add_u32_e32 v120, 0x4a, v112
	v_add_u32_e32 v121, 0x4b, v112
	v_cndmask_b32_e32 v116, v229, v98, vcc
	v_cmp_le_i32_e32 vcc, v117, v212
	v_add_u32_e32 v122, 0x50, v112
	v_add_u32_e32 v123, 0x51, v112
	v_cndmask_b32_e32 v117, v229, v99, vcc
	v_cmp_le_i32_e32 vcc, v118, v212
	v_add_u32_e32 v124, 0x52, v112
	v_add_u32_e32 v125, 0x53, v112
	v_cndmask_b32_e32 v118, v229, v100, vcc
	v_cmp_le_i32_e32 vcc, v119, v212
	v_add_u32_e32 v126, 0x58, v112
	v_add_u32_e32 v127, 0x59, v112
	v_cndmask_b32_e32 v119, v229, v101, vcc
	v_cmp_le_i32_e32 vcc, v120, v212
	v_add_u32_e32 v172, 0x5a, v112
	v_add_u32_e32 v173, 0x5b, v112
	v_cndmask_b32_e32 v120, v229, v102, vcc
	v_cmp_le_i32_e32 vcc, v121, v212
	v_add_u32_e32 v174, 0x60, v112
	v_max3_f32 v115, v114, s49, v113
	v_cndmask_b32_e32 v121, v229, v103, vcc
	v_cmp_le_i32_e32 vcc, v122, v212
	v_max3_f32 v115, v115, v116, v117
	v_max3_f32 v115, v115, v118, v119
	v_cndmask_b32_e32 v122, v229, v104, vcc
	v_cmp_le_i32_e32 vcc, v123, v212
	v_max3_f32 v115, v115, v120, v121
	v_and_b32_e32 v175, 64, v228
	v_cndmask_b32_e32 v123, v229, v105, vcc
	v_cmp_le_i32_e32 vcc, v124, v212
	v_max3_f32 v115, v115, v122, v123
	v_add_u32_e32 v175, 64, v175
	v_cndmask_b32_e32 v124, v229, v106, vcc
	v_cmp_le_i32_e32 vcc, v125, v212
	s_mov_b64 s[42:43], 0
	s_nop 0
	v_cndmask_b32_e32 v125, v229, v107, vcc
	v_cmp_le_i32_e32 vcc, v126, v212
	v_max3_f32 v115, v115, v124, v125
	s_nop 0
	v_cndmask_b32_e32 v126, v229, v108, vcc
	v_cmp_le_i32_e32 vcc, v127, v212
	s_nop 1
	v_cndmask_b32_e32 v127, v229, v109, vcc
	v_cmp_le_i32_e32 vcc, v172, v212
	v_max3_f32 v115, v115, v126, v127
	s_nop 0
	v_cndmask_b32_e32 v172, v229, v110, vcc
	v_cmp_le_i32_e32 vcc, v173, v212
	s_nop 1
	v_cndmask_b32_e32 v173, v229, v111, vcc
	v_cmp_le_i32_e32 vcc, v174, v212
	v_add_u32_e32 v174, 0x61, v112
	v_max3_f32 v115, v115, v172, v173
	v_cndmask_b32_e32 v164, v229, v80, vcc
	v_cmp_le_i32_e32 vcc, v174, v212
	v_add_u32_e32 v174, 0x62, v112
	s_nop 0
	v_cndmask_b32_e32 v165, v229, v81, vcc
	v_cmp_le_i32_e32 vcc, v174, v212
	v_add_u32_e32 v174, 0x63, v112
	v_max3_f32 v115, v115, v164, v165
	v_cndmask_b32_e32 v166, v229, v82, vcc
	v_cmp_le_i32_e32 vcc, v174, v212
	v_add_u32_e32 v174, 0x68, v112
	s_nop 0
	v_cndmask_b32_e32 v167, v229, v83, vcc
	v_cmp_le_i32_e32 vcc, v174, v212
	v_add_u32_e32 v174, 0x69, v112
	v_max3_f32 v115, v115, v166, v167
	v_cndmask_b32_e32 v160, v229, v84, vcc
	v_cmp_le_i32_e32 vcc, v174, v212
	v_add_u32_e32 v174, 0x6a, v112
	s_nop 0
	v_cndmask_b32_e32 v161, v229, v85, vcc
	v_cmp_le_i32_e32 vcc, v174, v212
	v_add_u32_e32 v174, 0x6b, v112
	v_max3_f32 v115, v115, v160, v161
	v_cndmask_b32_e32 v162, v229, v86, vcc
	v_cmp_le_i32_e32 vcc, v174, v212
	v_add_u32_e32 v174, 0x70, v112
	s_nop 0
	v_cndmask_b32_e32 v163, v229, v87, vcc
	v_cmp_le_i32_e32 vcc, v174, v212
	v_add_u32_e32 v174, 0x71, v112
	v_max3_f32 v115, v115, v162, v163
	v_cndmask_b32_e32 v208, v229, v88, vcc
	v_cmp_le_i32_e32 vcc, v174, v212
	v_add_u32_e32 v174, 0x72, v112
	s_nop 0
	v_cndmask_b32_e32 v209, v229, v89, vcc
	v_cmp_le_i32_e32 vcc, v174, v212
	v_add_u32_e32 v174, 0x73, v112
	v_max3_f32 v115, v115, v208, v209
	v_cndmask_b32_e32 v210, v229, v90, vcc
	v_cmp_le_i32_e32 vcc, v174, v212
	v_add_u32_e32 v174, 0x78, v112
	s_nop 0
	v_cndmask_b32_e32 v211, v229, v91, vcc
	v_cmp_le_i32_e32 vcc, v174, v212
	v_add_u32_e32 v174, 0x79, v112
	v_max3_f32 v115, v115, v210, v211
	v_cndmask_b32_e32 v226, v229, v92, vcc
	v_cmp_le_i32_e32 vcc, v174, v212
	v_add_u32_e32 v174, 0x7a, v112
	v_add_u32_e32 v112, 0x7b, v112
	v_cndmask_b32_e32 v252, v229, v93, vcc
	v_cmp_le_i32_e32 vcc, v174, v212
	v_xor_b32_e32 v174, 32, v228
	v_max3_f32 v115, v115, v226, v252
	v_cndmask_b32_e32 v253, v229, v94, vcc
	v_cmp_le_i32_e32 vcc, v112, v212
	s_nop 1
	v_cndmask_b32_e32 v112, v229, v95, vcc
	v_cmp_lt_i32_e32 vcc, v174, v175
	v_max3_f32 v115, v115, v253, v112
	s_nop 0
	v_cndmask_b32_e32 v174, v228, v174, vcc
	v_lshlrev_b32_e32 v174, 2, v174
	ds_bpermute_b32 v174, v174, v115
	s_waitcnt lgkmcnt(0)
	v_max_f32_e32 v174, v174, v174
	v_max_f32_e32 v251, v115, v174
	v_sub_f32_e32 v114, v114, v251
	v_sub_f32_e32 v113, v113, v251
	v_exp_f32_e32 v114, v114
	v_exp_f32_e32 v113, v113
	v_sub_f32_e32 v115, v116, v251
	v_exp_f32_e32 v115, v115
	v_sub_f32_e32 v116, v117, v251
	v_exp_f32_e32 v116, v116
	v_sub_f32_e32 v117, v118, v251
	v_sub_f32_e32 v118, v119, v251
	v_sub_f32_e32 v119, v120, v251
	v_sub_f32_e32 v120, v121, v251
	v_sub_f32_e32 v121, v122, v251
	v_sub_f32_e32 v122, v123, v251
	v_sub_f32_e32 v123, v124, v251
	v_sub_f32_e32 v124, v125, v251
	v_sub_f32_e32 v125, v126, v251
	v_sub_f32_e32 v126, v127, v251
	v_sub_f32_e32 v127, v172, v251
	v_sub_f32_e32 v172, v173, v251
	v_exp_f32_e32 v117, v117
	v_exp_f32_e32 v254, v172
	v_cvt_pk_bf16_f32 v172, v114, v113
	v_add_f32_e32 v114, 0, v114
	v_exp_f32_e32 v118, v118
	v_add_f32_e32 v113, v113, v114
	v_exp_f32_e32 v119, v119
	v_add_f32_e32 v113, v115, v113
	v_exp_f32_e32 v120, v120
	v_add_f32_e32 v113, v116, v113
	v_exp_f32_e32 v121, v121
	v_add_f32_e32 v113, v117, v113
	v_exp_f32_e32 v122, v122
	v_add_f32_e32 v113, v118, v113
	v_exp_f32_e32 v123, v123
	v_add_f32_e32 v113, v119, v113
	v_exp_f32_e32 v124, v124
	v_add_f32_e32 v113, v120, v113
	v_exp_f32_e32 v125, v125
	v_add_f32_e32 v113, v121, v113
	v_exp_f32_e32 v126, v126
	v_add_f32_e32 v113, v122, v113
	v_exp_f32_e32 v127, v127
	v_add_f32_e32 v113, v123, v113
	v_add_f32_e32 v113, v124, v113
	v_sub_f32_e32 v114, v164, v251
	v_cvt_pk_bf16_f32 v173, v115, v116
	v_add_f32_e32 v113, v125, v113
	v_exp_f32_e32 v114, v114
	v_sub_f32_e32 v115, v165, v251
	v_add_f32_e32 v113, v126, v113
	v_exp_f32_e32 v115, v115
	v_sub_f32_e32 v116, v166, v251
	v_cvt_pk_bf16_f32 v174, v117, v118
	v_add_f32_e32 v113, v127, v113
	v_exp_f32_e32 v116, v116
	v_sub_f32_e32 v117, v167, v251
	v_add_f32_e32 v113, v254, v113
	v_exp_f32_e32 v117, v117
	v_sub_f32_e32 v118, v160, v251
	v_sub_f32_e32 v112, v112, v251
	v_cvt_pk_bf16_f32 v175, v119, v120
	v_cvt_pk_bf16_f32 v169, v123, v124
	v_exp_f32_e32 v118, v118
	v_sub_f32_e32 v119, v161, v251
	v_sub_f32_e32 v123, v209, v251
	v_exp_f32_e32 v209, v112
	v_add_f32_e32 v112, v114, v113
	v_exp_f32_e32 v119, v119
	v_sub_f32_e32 v120, v162, v251
	v_add_f32_e32 v112, v115, v112
	v_cvt_pk_bf16_f32 v168, v121, v122
	v_exp_f32_e32 v120, v120
	v_sub_f32_e32 v121, v163, v251
	v_add_f32_e32 v112, v116, v112
	v_exp_f32_e32 v121, v121
	v_sub_f32_e32 v122, v208, v251
	v_add_f32_e32 v112, v117, v112
	v_exp_f32_e32 v122, v122
	v_add_f32_e32 v112, v118, v112
	v_exp_f32_e32 v123, v123
	v_sub_f32_e32 v124, v210, v251
	v_add_f32_e32 v112, v119, v112
	v_cvt_pk_bf16_f32 v170, v125, v126
	v_exp_f32_e32 v124, v124
	v_sub_f32_e32 v125, v211, v251
	v_add_f32_e32 v112, v120, v112
	v_exp_f32_e32 v125, v125
	v_sub_f32_e32 v126, v226, v251
	v_add_f32_e32 v112, v121, v112
	v_cvt_pk_bf16_f32 v171, v127, v254
	v_exp_f32_e32 v126, v126
	v_sub_f32_e32 v127, v252, v251
	v_add_f32_e32 v112, v122, v112
	v_exp_f32_e32 v127, v127
	v_sub_f32_e32 v164, v253, v251
	v_add_f32_e32 v112, v123, v112
	v_exp_f32_e32 v208, v164
	v_add_f32_e32 v112, v124, v112
	v_add_f32_e32 v112, v125, v112
	v_add_f32_e32 v112, v126, v112
	v_add_f32_e32 v112, v127, v112
	v_add_f32_e32 v113, v208, v112
	v_xor_b32_e32 v112, 0x80000000, v251
	v_cvt_pk_bf16_f32 v164, v114, v115
	v_cvt_pk_bf16_f32 v165, v116, v117
	v_cvt_pk_bf16_f32 v166, v118, v119
	v_cvt_pk_bf16_f32 v167, v120, v121
	v_cvt_pk_bf16_f32 v160, v122, v123
	v_cvt_pk_bf16_f32 v161, v124, v125
	v_cvt_pk_bf16_f32 v162, v126, v127
	v_cvt_pk_bf16_f32 v163, v208, v209
	v_add_f32_e32 v252, v209, v113
	v_mov_b32_e32 v113, v112
	v_mov_b32_e32 v114, v112
	v_mov_b32_e32 v115, v112
	v_mov_b32_e32 v116, v112
	v_mov_b32_e32 v117, v112
	v_mov_b32_e32 v118, v112
	v_mov_b32_e32 v119, v112
	v_mov_b32_e32 v120, v112
	v_mov_b32_e32 v121, v112
	v_mov_b32_e32 v122, v112
	v_mov_b32_e32 v123, v112
	v_mov_b32_e32 v124, v112
	v_mov_b32_e32 v125, v112
	v_mov_b32_e32 v126, v112
	v_mov_b32_e32 v127, v112

.Ldfu_565:
	ds_read_b128 v[124:127], v247 offset:4608
	ds_read_b128 v[120:123], v247 offset:4640
	ds_read_b128 v[116:119], v247 offset:4672
	ds_read_b128 v[112:115], v247 offset:4704
	v_mfma_f32_32x32x16_bf16 v[48:63], v[188:191], v[192:195], v[48:63]
	v_max3_f32 v172, v96, s49, v97
	v_max3_f32 v172, v172, v98, v99
	v_max3_f32 v172, v172, v100, v101
	v_max3_f32 v172, v172, v102, v103
	v_mfma_f32_32x32x16_bf16 v[48:63], v[184:187], v[196:199], v[48:63]
	v_max3_f32 v188, v172, v104, v105
	v_max3_f32 v188, v188, v106, v107
	v_max3_f32 v188, v188, v108, v109
	v_max3_f32 v188, v188, v110, v111
	v_mfma_f32_32x32x16_bf16 v[48:63], v[180:183], v[200:203], v[48:63]
	v_max3_f32 v184, v188, v80, v81
	v_max3_f32 v184, v184, v82, v83
	v_max3_f32 v184, v184, v84, v85
	v_max3_f32 v184, v184, v86, v87
	v_max3_f32 v180, v184, v88, v89
	v_max3_f32 v180, v180, v90, v91
	v_max3_f32 v180, v180, v92, v93
	v_mfma_f32_32x32x16_bf16 v[48:63], v[176:179], v[204:207], v[48:63]
	v_max3_f32 v180, v180, v94, v95
	v_mov_b32_e32 v181, v180
	s_nop 1
	v_permlane32_swap_b32_e32 v180, v181
	v_max_f32_e32 v176, v181, v181
	v_max_f32_e32 v177, v180, v180
	v_max_f32_e32 v176, v177, v176
	v_cmp_ge_f32_e32 vcc, s50, v176
	s_cmp_eq_u64 vcc, exec
	v_mov_b32_e32 v224, 1.0
	s_cbranch_scc1 .Ldfu_567
	v_max_f32_e32 v64, v176, v176
	v_max_f32_e32 v65, 0, v64
	v_exp_f32_e64 v224, -v65
	v_add_f32_e32 v249, v249, v65
	v_xor_b32_e32 v64, 0x80000000, v249
	v_sub_f32_e32 v96, v96, v65
	v_sub_f32_e32 v97, v97, v65
	v_sub_f32_e32 v98, v98, v65
	v_sub_f32_e32 v99, v99, v65
	v_sub_f32_e32 v100, v100, v65
	v_sub_f32_e32 v101, v101, v65
	v_sub_f32_e32 v102, v102, v65
	v_sub_f32_e32 v103, v103, v65
	v_sub_f32_e32 v104, v104, v65
	v_sub_f32_e32 v105, v105, v65
	v_sub_f32_e32 v106, v106, v65
	v_sub_f32_e32 v107, v107, v65
	v_sub_f32_e32 v108, v108, v65
	v_sub_f32_e32 v109, v109, v65
	v_sub_f32_e32 v110, v110, v65
	v_sub_f32_e32 v111, v111, v65
	v_sub_f32_e32 v80, v80, v65
	v_sub_f32_e32 v81, v81, v65
	v_sub_f32_e32 v82, v82, v65
	v_sub_f32_e32 v83, v83, v65
	v_sub_f32_e32 v84, v84, v65
	v_sub_f32_e32 v85, v85, v65
	v_sub_f32_e32 v86, v86, v65
	v_sub_f32_e32 v87, v87, v65
	v_sub_f32_e32 v88, v88, v65
	v_sub_f32_e32 v89, v89, v65
	v_sub_f32_e32 v90, v90, v65
	v_sub_f32_e32 v91, v91, v65
	v_sub_f32_e32 v92, v92, v65
	v_sub_f32_e32 v93, v93, v65
	v_sub_f32_e32 v94, v94, v65
	v_sub_f32_e32 v95, v95, v65
	v_mov_b32_e32 v65, v64
	v_mov_b32_e32 v66, v64
	v_mov_b32_e32 v67, v64
	v_mov_b32_e32 v68, v64
	v_mov_b32_e32 v69, v64
	v_mov_b32_e32 v70, v64
	v_mov_b32_e32 v71, v64
	v_mov_b32_e32 v72, v64
	v_mov_b32_e32 v73, v64
	v_mov_b32_e32 v74, v64
	v_mov_b32_e32 v75, v64
	v_mov_b32_e32 v76, v64
	v_mov_b32_e32 v77, v64
	v_mov_b32_e32 v78, v64
	v_mov_b32_e32 v79, v64
.Ldfu_567:
	s_waitcnt lgkmcnt(3)
	v_mfma_f32_32x32x16_bf16 v[32:47], v[124:127], v[192:195], v[32:47]
	ds_read_b128 v[188:191], v247 offset:9216
	ds_read_b128 v[184:187], v247 offset:9248
	ds_read_b128 v[180:183], v247 offset:9280
	ds_read_b128 v[176:179], v247 offset:9312
	v_exp_f32_e32 v164, v96
	v_exp_f32_e32 v165, v97
	v_exp_f32_e32 v166, v98
	v_exp_f32_e32 v167, v99
	v_cvt_pk_bf16_f32 v172, v164, v165
	v_cvt_pk_bf16_f32 v173, v166, v167
	s_waitcnt lgkmcnt(6)
	v_mfma_f32_32x32x16_bf16 v[32:47], v[120:123], v[196:199], v[32:47]
	v_exp_f32_e32 v124, v100
	v_exp_f32_e32 v125, v101
	v_exp_f32_e32 v126, v102
	v_exp_f32_e32 v127, v103
	v_cvt_pk_bf16_f32 v174, v124, v125
	v_cvt_pk_bf16_f32 v175, v126, v127
	s_waitcnt lgkmcnt(5)
	v_mfma_f32_32x32x16_bf16 v[32:47], v[116:119], v[200:203], v[32:47]
	v_exp_f32_e32 v120, v104
	v_exp_f32_e32 v121, v105
	v_exp_f32_e32 v122, v106
	v_exp_f32_e32 v123, v107
	v_cvt_pk_bf16_f32 v168, v120, v121
	v_cvt_pk_bf16_f32 v169, v122, v123
	s_waitcnt lgkmcnt(4)
	v_mfma_f32_32x32x16_bf16 v[32:47], v[112:115], v[204:207], v[32:47]
	v_exp_f32_e32 v116, v108
	v_exp_f32_e32 v117, v109
	v_exp_f32_e32 v118, v110
	v_exp_f32_e32 v119, v111
	v_cvt_pk_bf16_f32 v170, v116, v117
	v_cvt_pk_bf16_f32 v171, v118, v119
	v_add_f32_e32 v112, v166, v164
	v_add_f32_e32 v113, v167, v165
	s_waitcnt lgkmcnt(3)
	v_mfma_f32_32x32x16_bf16 v[16:31], v[188:191], v[192:195], v[16:31]
	v_add_f32_e32 v112, v124, v112
	v_add_f32_e32 v113, v125, v113
	ds_read_b128 v[96:99], v247 offset:13824
	ds_read_b128 v[100:103], v247 offset:13856
	ds_read_b128 v[104:107], v247 offset:13888
	ds_read_b128 v[108:111], v247 offset:13920
	v_add_f32_e32 v112, v126, v112
	v_add_f32_e32 v113, v127, v113
	v_exp_f32_e32 v80, v80
	v_exp_f32_e32 v81, v81
	v_add_f32_e32 v112, v120, v112
	v_add_f32_e32 v113, v121, v113
	v_cvt_pk_bf16_f32 v164, v80, v81
	v_add_f32_e32 v112, v122, v112
	v_add_f32_e32 v113, v123, v113
	v_add_f32_e32 v112, v116, v112
	v_add_f32_e32 v113, v117, v113
	v_add_f32_e32 v112, v118, v112
	v_add_f32_e32 v113, v119, v113
	v_add_f32_e32 v112, v80, v112
	v_add_f32_e32 v113, v81, v113
	s_waitcnt lgkmcnt(6)
	v_mfma_f32_32x32x16_bf16 v[16:31], v[184:187], v[196:199], v[16:31]
	v_exp_f32_e32 v80, v82
	v_exp_f32_e32 v81, v83
	v_add_f32_e32 v82, v80, v112
	v_cvt_pk_bf16_f32 v165, v80, v81
	v_add_f32_e32 v83, v81, v113
	s_waitcnt lgkmcnt(5)
	v_mfma_f32_32x32x16_bf16 v[16:31], v[180:183], v[200:203], v[16:31]
	v_exp_f32_e32 v80, v84
	v_exp_f32_e32 v81, v85
	v_add_f32_e32 v82, v80, v82
	v_cvt_pk_bf16_f32 v166, v80, v81
	v_add_f32_e32 v83, v81, v83
	s_waitcnt lgkmcnt(4)
	v_mfma_f32_32x32x16_bf16 v[16:31], v[176:179], v[204:207], v[16:31]
	v_exp_f32_e32 v80, v86
	v_exp_f32_e32 v81, v87
	v_add_f32_e32 v82, v80, v82
	v_cvt_pk_bf16_f32 v167, v80, v81
	v_add_f32_e32 v83, v81, v83
	s_waitcnt lgkmcnt(3)
	v_mfma_f32_32x32x16_bf16 v[0:15], v[96:99], v[192:195], v[0:15]
	v_exp_f32_e32 v80, v88
	v_exp_f32_e32 v81, v89
	v_add_f32_e32 v82, v80, v82
	v_cvt_pk_bf16_f32 v160, v80, v81
	v_add_f32_e32 v83, v81, v83
	s_waitcnt lgkmcnt(2)
	v_mfma_f32_32x32x16_bf16 v[0:15], v[100:103], v[196:199], v[0:15]
	v_exp_f32_e32 v80, v90
	v_exp_f32_e32 v81, v91
	v_add_f32_e32 v82, v80, v82
	v_cvt_pk_bf16_f32 v161, v80, v81
	v_add_f32_e32 v83, v81, v83
	s_waitcnt lgkmcnt(1)
	v_mfma_f32_32x32x16_bf16 v[0:15], v[104:107], v[200:203], v[0:15]
	v_exp_f32_e32 v80, v92
	v_exp_f32_e32 v81, v93
	v_add_f32_e32 v82, v80, v82
	v_cvt_pk_bf16_f32 v162, v80, v81
	v_add_f32_e32 v83, v81, v83
	s_waitcnt lgkmcnt(0)
	v_mfma_f32_32x32x16_bf16 v[0:15], v[108:111], v[204:207], v[0:15]
	v_exp_f32_e32 v80, v94
	v_exp_f32_e32 v81, v95
	v_add_f32_e32 v82, v80, v82
	v_cvt_pk_bf16_f32 v163, v80, v81
	v_add_f32_e32 v83, v81, v83
	v_add_f32_e32 v252, v82, v83
	v_fmac_f32_e32 v252, v223, v224
	s_branch .Ldfu_570
.Ldfu_568:
	v_mov_b64_e32 v[162:163], v[206:207]
	v_mov_b64_e32 v[166:167], v[202:203]
	v_mov_b64_e32 v[170:171], v[198:199]
	v_mov_b64_e32 v[174:175], v[194:195]
	v_mov_b64_e32 v[160:161], v[204:205]
	v_mov_b64_e32 v[164:165], v[200:201]
	v_mov_b64_e32 v[168:169], v[196:197]
	v_mov_b64_e32 v[172:173], v[192:193]
	s_andn2_b64 vcc, exec, s[40:41]
	s_cbranch_vccz .Ldfu_571
	s_branch .LBB0_554
.Ldfu_569:
	v_mov_b64_e32 v[64:65], v[112:113]
	v_mov_b32_e32 v207, v163
	v_mov_b32_e32 v206, v162
	v_mov_b32_e32 v205, v161
	v_mov_b32_e32 v204, v160
	v_mov_b32_e32 v203, v167
	v_mov_b32_e32 v202, v166
	v_mov_b32_e32 v201, v165
	v_mov_b32_e32 v200, v164
	v_mov_b32_e32 v199, v171
	v_mov_b32_e32 v198, v170
	v_mov_b32_e32 v197, v169
	v_mov_b32_e32 v196, v168
	v_mov_b32_e32 v195, v175
	v_mov_b32_e32 v194, v174
	v_mov_b32_e32 v193, v173
	v_mov_b32_e32 v192, v172
	v_mov_b32_e32 v249, v251
	v_mov_b32_e32 v224, 1.0
	v_mov_b64_e32 v[66:67], v[114:115]
	v_mov_b64_e32 v[68:69], v[116:117]
	v_mov_b64_e32 v[70:71], v[118:119]
	v_mov_b64_e32 v[72:73], v[120:121]
	v_mov_b64_e32 v[74:75], v[122:123]
	v_mov_b64_e32 v[76:77], v[124:125]
	v_mov_b64_e32 v[78:79], v[126:127]

.Ldfu_exit_b:
	v_mov_b32_e32 v204, v160
	v_mov_b32_e32 v205, v161
	v_mov_b32_e32 v206, v162
	v_mov_b32_e32 v207, v163
	v_mov_b32_e32 v200, v164
	v_mov_b32_e32 v201, v165
	v_mov_b32_e32 v202, v166
	v_mov_b32_e32 v203, v167
	v_mov_b32_e32 v196, v168
	v_mov_b32_e32 v197, v169
	v_mov_b32_e32 v198, v170
	v_mov_b32_e32 v199, v171
	v_mov_b32_e32 v192, v172
	v_mov_b32_e32 v193, v173
	v_mov_b32_e32 v194, v174
	v_mov_b32_e32 v195, v175
	s_branch .LBB0_572
